# rmsnorm rows split unevenly between block halves (blocks 0-127 which also build rope tables and bias partials take 1 batch per wave, blocks 128-255 take 7)
# baseline (speedup 1.0000x reference)
.Ltcx_done:
	s_lshl_b32 s3, s2, 5
	s_add_u32 s46, s52, 0x1aa0800
	s_addc_u32 s47, s53, 0
	s_lshl_b32 s54, s33, 5
	s_mov_b64 s[8:9], exec
	v_readfirstlane_b32 s4, v238
	v_and_b32_e32 v2, 63, v238
	v_lshlrev_b32_e32 v22, 5, v2
	v_lshlrev_b32_e32 v23, 4, v2
	v_xor_b32_e32 v16, 32, v2
	v_xor_b32_e32 v17, 16, v2
	v_xor_b32_e32 v18, 8, v2
	v_xor_b32_e32 v19, 4, v2
	v_xor_b32_e32 v20, 2, v2
	v_xor_b32_e32 v21, 1, v2
	v_lshlrev_b32_e32 v16, 2, v16
	v_lshlrev_b32_e32 v17, 2, v17
	v_lshlrev_b32_e32 v18, 2, v18
	v_lshlrev_b32_e32 v19, 2, v19
	v_lshlrev_b32_e32 v20, 2, v20
	v_lshlrev_b32_e32 v21, 2, v21
	v_mov_b32_e32 v220, 0x358637bd
	s_lshr_b32 s4, s4, 6
	s_and_b32 s11, s2, 127
	s_lshl_b32 s11, s11, 5
	s_lshl_b32 s16, s4, 2
	s_add_i32 s16, s16, s11
	s_mov_b32 s5, 0x8000
	s_cmp_lt_u32 s2, 128
	s_cselect_b32 s5, 0x1000, s5
	s_cselect_b32 s11, 0, 0x1000
	s_add_i32 s16, s16, s11
	s_mov_b32 s10, 0x1000
	s_cmp_lt_u32 s16, s5
	s_cbranch_scc0 .Lrms_done
	global_load_dwordx4 v[100:103], v22, s[14:15]
	global_load_dwordx4 v[104:107], v22, s[14:15] offset:16
	global_load_dwordx4 v[108:111], v22, s[14:15] offset:2048
	global_load_dwordx4 v[112:115], v22, s[14:15] offset:2064
	s_mov_b32 s7, 0x800000
	s_lshl_b32 s6, s16, 12
	s_add_u32 s18, s12, s6
	s_addc_u32 s19, s13, 0
	s_add_u32 s20, s18, 0x1000
	s_addc_u32 s21, s19, 0
	s_add_u32 s22, s20, 0x1000
	s_addc_u32 s23, s21, 0
	s_add_u32 s24, s22, 0x1000
	s_addc_u32 s25, s23, 0
	global_load_dwordx4 v[116:119], v22, s[18:19]
	global_load_dwordx4 v[120:123], v22, s[18:19] offset:16
	global_load_dwordx4 v[124:127], v22, s[18:19] offset:2048
	global_load_dwordx4 v[128:131], v22, s[18:19] offset:2064
	global_load_dwordx4 v[132:135], v22, s[20:21]
	global_load_dwordx4 v[136:139], v22, s[20:21] offset:16
	global_load_dwordx4 v[140:143], v22, s[20:21] offset:2048
	global_load_dwordx4 v[144:147], v22, s[20:21] offset:2064
	global_load_dwordx4 v[148:151], v22, s[22:23]
	global_load_dwordx4 v[152:155], v22, s[22:23] offset:16
	global_load_dwordx4 v[156:159], v22, s[22:23] offset:2048
	global_load_dwordx4 v[160:163], v22, s[22:23] offset:2064
	global_load_dwordx4 v[164:167], v22, s[24:25]
	global_load_dwordx4 v[168:171], v22, s[24:25] offset:16
	global_load_dwordx4 v[172:175], v22, s[24:25] offset:2048
	global_load_dwordx4 v[176:179], v22, s[24:25] offset:2064
	s_add_i32 s17, s16, s10
	s_cmp_lt_u32 s17, s5
	s_cbranch_scc0 .Lrms_f_last
	s_lshl_b32 s6, s17, 12
	s_add_u32 s18, s12, s6
	s_addc_u32 s19, s13, 0
	s_add_u32 s20, s18, 0x1000
	s_addc_u32 s21, s19, 0
	s_add_u32 s22, s20, 0x1000
	s_addc_u32 s23, s21, 0
	s_add_u32 s24, s22, 0x1000
	s_addc_u32 s25, s23, 0
	global_load_dwordx4 v[24:27], v22, s[18:19]
	global_load_dwordx4 v[28:31], v22, s[18:19] offset:16
	global_load_dwordx4 v[32:35], v22, s[18:19] offset:2048
	global_load_dwordx4 v[36:39], v22, s[18:19] offset:2064
	global_load_dwordx4 v[40:43], v22, s[20:21]
	global_load_dwordx4 v[44:47], v22, s[20:21] offset:16
	global_load_dwordx4 v[48:51], v22, s[20:21] offset:2048
	global_load_dwordx4 v[52:55], v22, s[20:21] offset:2064
	global_load_dwordx4 v[56:59], v22, s[22:23]
	global_load_dwordx4 v[60:63], v22, s[22:23] offset:16
	global_load_dwordx4 v[64:67], v22, s[22:23] offset:2048
	global_load_dwordx4 v[68:71], v22, s[22:23] offset:2064
	global_load_dwordx4 v[72:75], v22, s[24:25]
	global_load_dwordx4 v[76:79], v22, s[24:25] offset:16
	global_load_dwordx4 v[80:83], v22, s[24:25] offset:2048
	global_load_dwordx4 v[84:87], v22, s[24:25] offset:2064
	s_waitcnt vmcnt(16)
	v_mul_f32_e32 v8, v116, v116
	v_mul_f32_e32 v9, v132, v132
	v_mul_f32_e32 v10, v148, v148
	v_mul_f32_e32 v11, v164, v164
	v_fmac_f32_e32 v8, v117, v117
	v_fmac_f32_e32 v9, v133, v133
	v_fmac_f32_e32 v10, v149, v149
	v_fmac_f32_e32 v11, v165, v165
	v_fmac_f32_e32 v8, v118, v118
	v_fmac_f32_e32 v9, v134, v134
	v_fmac_f32_e32 v10, v150, v150
	v_fmac_f32_e32 v11, v166, v166
	v_fmac_f32_e32 v8, v119, v119
	v_fmac_f32_e32 v9, v135, v135
	v_fmac_f32_e32 v10, v151, v151
	v_fmac_f32_e32 v11, v167, v167
	v_fmac_f32_e32 v8, v120, v120
	v_fmac_f32_e32 v9, v136, v136
	v_fmac_f32_e32 v10, v152, v152
	v_fmac_f32_e32 v11, v168, v168
	v_fmac_f32_e32 v8, v121, v121
	v_fmac_f32_e32 v9, v137, v137
	v_fmac_f32_e32 v10, v153, v153
	v_fmac_f32_e32 v11, v169, v169
	v_fmac_f32_e32 v8, v122, v122
	v_fmac_f32_e32 v9, v138, v138
	v_fmac_f32_e32 v10, v154, v154
	v_fmac_f32_e32 v11, v170, v170
	v_fmac_f32_e32 v8, v123, v123
	v_fmac_f32_e32 v9, v139, v139
	v_fmac_f32_e32 v10, v155, v155
	v_fmac_f32_e32 v11, v171, v171
	v_fmac_f32_e32 v8, v124, v124
	v_fmac_f32_e32 v9, v140, v140
	v_fmac_f32_e32 v10, v156, v156
	v_fmac_f32_e32 v11, v172, v172
	v_fmac_f32_e32 v8, v125, v125
	v_fmac_f32_e32 v9, v141, v141
	v_fmac_f32_e32 v10, v157, v157
	v_fmac_f32_e32 v11, v173, v173
	v_fmac_f32_e32 v8, v126, v126
	v_fmac_f32_e32 v9, v142, v142
	v_fmac_f32_e32 v10, v158, v158
	v_fmac_f32_e32 v11, v174, v174
	v_fmac_f32_e32 v8, v127, v127
	v_fmac_f32_e32 v9, v143, v143
	v_fmac_f32_e32 v10, v159, v159
	v_fmac_f32_e32 v11, v175, v175
	v_fmac_f32_e32 v8, v128, v128
	v_fmac_f32_e32 v9, v144, v144
	v_fmac_f32_e32 v10, v160, v160
	v_fmac_f32_e32 v11, v176, v176
	v_fmac_f32_e32 v8, v129, v129
	v_fmac_f32_e32 v9, v145, v145
	v_fmac_f32_e32 v10, v161, v161
	v_fmac_f32_e32 v11, v177, v177
	v_fmac_f32_e32 v8, v130, v130
	v_fmac_f32_e32 v9, v146, v146
	v_fmac_f32_e32 v10, v162, v162
	v_fmac_f32_e32 v11, v178, v178
	v_fmac_f32_e32 v8, v131, v131
	v_fmac_f32_e32 v9, v147, v147
	v_fmac_f32_e32 v10, v163, v163
	v_fmac_f32_e32 v11, v179, v179
	ds_bpermute_b32 v12, v16, v8
	ds_bpermute_b32 v13, v16, v9
	ds_bpermute_b32 v14, v16, v10
	ds_bpermute_b32 v15, v16, v11
	s_waitcnt lgkmcnt(0)
	v_add_f32_e32 v8, v8, v12
	v_add_f32_e32 v9, v9, v13
	v_add_f32_e32 v10, v10, v14
	v_add_f32_e32 v11, v11, v15
	ds_bpermute_b32 v12, v17, v8
	ds_bpermute_b32 v13, v17, v9
	ds_bpermute_b32 v14, v17, v10
	ds_bpermute_b32 v15, v17, v11
	s_waitcnt lgkmcnt(0)
	v_add_f32_e32 v8, v8, v12
	v_add_f32_e32 v9, v9, v13
	v_add_f32_e32 v10, v10, v14
	v_add_f32_e32 v11, v11, v15
	ds_bpermute_b32 v12, v18, v8
	ds_bpermute_b32 v13, v18, v9
	ds_bpermute_b32 v14, v18, v10
	ds_bpermute_b32 v15, v18, v11
	s_waitcnt lgkmcnt(0)
	v_add_f32_e32 v8, v8, v12
	v_add_f32_e32 v9, v9, v13
	v_add_f32_e32 v10, v10, v14
	v_add_f32_e32 v11, v11, v15
	ds_bpermute_b32 v12, v19, v8
	ds_bpermute_b32 v13, v19, v9
	ds_bpermute_b32 v14, v19, v10
	ds_bpermute_b32 v15, v19, v11
	s_waitcnt lgkmcnt(0)
	v_add_f32_e32 v8, v8, v12
	v_add_f32_e32 v9, v9, v13
	v_add_f32_e32 v10, v10, v14
	v_add_f32_e32 v11, v11, v15
	ds_bpermute_b32 v12, v20, v8
	ds_bpermute_b32 v13, v20, v9
	ds_bpermute_b32 v14, v20, v10
	ds_bpermute_b32 v15, v20, v11
	s_waitcnt lgkmcnt(0)
	v_add_f32_e32 v8, v8, v12
	v_add_f32_e32 v9, v9, v13
	v_add_f32_e32 v10, v10, v14
	v_add_f32_e32 v11, v11, v15
	ds_bpermute_b32 v12, v21, v8
	ds_bpermute_b32 v13, v21, v9
	ds_bpermute_b32 v14, v21, v10
	ds_bpermute_b32 v15, v21, v11
	s_waitcnt lgkmcnt(0)
	v_add_f32_e32 v8, v8, v12
	v_add_f32_e32 v9, v9, v13
	v_add_f32_e32 v10, v10, v14
	v_add_f32_e32 v11, v11, v15
	v_fmamk_f32 v8, v8, 0x3a800000, v220
	v_fmamk_f32 v9, v9, 0x3a800000, v220
	v_fmamk_f32 v10, v10, 0x3a800000, v220
	v_fmamk_f32 v11, v11, 0x3a800000, v220
	v_mul_f32_e32 v12, 0x4b800000, v8
	v_mul_f32_e32 v13, 0x4b800000, v9
	v_mul_f32_e32 v14, 0x4b800000, v10
	v_mul_f32_e32 v15, 0x4b800000, v11
	v_cmp_gt_f32_e32 vcc, s7, v8
	s_nop 1
	v_cndmask_b32_e32 v8, v8, v12, vcc
	v_rsq_f32_e32 v212, v8
	s_nop 0
	v_mul_f32_e32 v216, 0x45800000, v212
	v_cndmask_b32_e32 v212, v212, v216, vcc
	v_cmp_gt_f32_e32 vcc, s7, v9
	s_nop 1
	v_cndmask_b32_e32 v9, v9, v13, vcc
	v_rsq_f32_e32 v213, v9
	s_nop 0
	v_mul_f32_e32 v216, 0x45800000, v213
	v_cndmask_b32_e32 v213, v213, v216, vcc
	v_cmp_gt_f32_e32 vcc, s7, v10
	s_nop 1
	v_cndmask_b32_e32 v10, v10, v14, vcc
	v_rsq_f32_e32 v214, v10
	s_nop 0
	v_mul_f32_e32 v216, 0x45800000, v214
	v_cndmask_b32_e32 v214, v214, v216, vcc
	v_cmp_gt_f32_e32 vcc, s7, v11
	s_nop 1
	v_cndmask_b32_e32 v11, v11, v15, vcc
	v_rsq_f32_e32 v215, v11
	s_nop 0
	v_mul_f32_e32 v216, 0x45800000, v215
	v_cndmask_b32_e32 v215, v215, v216, vcc
	s_lshl_b32 s6, s16, 11
	s_add_u32 s26, s46, s6
	s_addc_u32 s27, s47, 0
	s_add_u32 s30, s26, 0x1000
	s_addc_u32 s31, s27, 0
	v_mul_f32_e32 v116, v116, v212
	v_mul_f32_e32 v117, v117, v212
	v_mul_f32_e32 v118, v118, v212
	v_mul_f32_e32 v119, v119, v212
	v_mul_f32_e32 v120, v120, v212
	v_mul_f32_e32 v121, v121, v212
	v_mul_f32_e32 v122, v122, v212
	v_mul_f32_e32 v123, v123, v212
	v_mul_f32_e32 v124, v124, v212
	v_mul_f32_e32 v125, v125, v212
	v_mul_f32_e32 v126, v126, v212
	v_mul_f32_e32 v127, v127, v212
	v_mul_f32_e32 v128, v128, v212
	v_mul_f32_e32 v129, v129, v212
	v_mul_f32_e32 v130, v130, v212
	v_mul_f32_e32 v131, v131, v212
	v_mul_f32_e32 v116, v100, v116
	v_mul_f32_e32 v117, v101, v117
	v_mul_f32_e32 v118, v102, v118
	v_mul_f32_e32 v119, v103, v119
	v_mul_f32_e32 v120, v104, v120
	v_mul_f32_e32 v121, v105, v121
	v_mul_f32_e32 v122, v106, v122
	v_mul_f32_e32 v123, v107, v123
	v_mul_f32_e32 v124, v108, v124
	v_mul_f32_e32 v125, v109, v125
	v_mul_f32_e32 v126, v110, v126
	v_mul_f32_e32 v127, v111, v127
	v_mul_f32_e32 v128, v112, v128
	v_mul_f32_e32 v129, v113, v129
	v_mul_f32_e32 v130, v114, v130
	v_mul_f32_e32 v131, v115, v131
	v_cvt_pk_bf16_f32 v180, v116, v117
	v_cvt_pk_bf16_f32 v181, v118, v119
	v_cvt_pk_bf16_f32 v182, v120, v121
	v_cvt_pk_bf16_f32 v183, v122, v123
	v_cvt_pk_bf16_f32 v184, v124, v125
	v_cvt_pk_bf16_f32 v185, v126, v127
	v_cvt_pk_bf16_f32 v186, v128, v129
	v_cvt_pk_bf16_f32 v187, v130, v131
	global_store_dwordx4 v23, v[180:183], s[26:27]
	global_store_dwordx4 v23, v[184:187], s[26:27] offset:1024
	v_mul_f32_e32 v132, v132, v213
	v_mul_f32_e32 v133, v133, v213
	v_mul_f32_e32 v134, v134, v213
	v_mul_f32_e32 v135, v135, v213
	v_mul_f32_e32 v136, v136, v213
	v_mul_f32_e32 v137, v137, v213
	v_mul_f32_e32 v138, v138, v213
	v_mul_f32_e32 v139, v139, v213
	v_mul_f32_e32 v140, v140, v213
	v_mul_f32_e32 v141, v141, v213
	v_mul_f32_e32 v142, v142, v213
	v_mul_f32_e32 v143, v143, v213
	v_mul_f32_e32 v144, v144, v213
	v_mul_f32_e32 v145, v145, v213
	v_mul_f32_e32 v146, v146, v213
	v_mul_f32_e32 v147, v147, v213
	v_mul_f32_e32 v132, v100, v132
	v_mul_f32_e32 v133, v101, v133
	v_mul_f32_e32 v134, v102, v134
	v_mul_f32_e32 v135, v103, v135
	v_mul_f32_e32 v136, v104, v136
	v_mul_f32_e32 v137, v105, v137
	v_mul_f32_e32 v138, v106, v138
	v_mul_f32_e32 v139, v107, v139
	v_mul_f32_e32 v140, v108, v140
	v_mul_f32_e32 v141, v109, v141
	v_mul_f32_e32 v142, v110, v142
	v_mul_f32_e32 v143, v111, v143
	v_mul_f32_e32 v144, v112, v144
	v_mul_f32_e32 v145, v113, v145
	v_mul_f32_e32 v146, v114, v146
	v_mul_f32_e32 v147, v115, v147
	v_cvt_pk_bf16_f32 v188, v132, v133
	v_cvt_pk_bf16_f32 v189, v134, v135
	v_cvt_pk_bf16_f32 v190, v136, v137
	v_cvt_pk_bf16_f32 v191, v138, v139
	v_cvt_pk_bf16_f32 v192, v140, v141
	v_cvt_pk_bf16_f32 v193, v142, v143
	v_cvt_pk_bf16_f32 v194, v144, v145
	v_cvt_pk_bf16_f32 v195, v146, v147
	global_store_dwordx4 v23, v[188:191], s[26:27] offset:2048
	global_store_dwordx4 v23, v[192:195], s[26:27] offset:3072
	v_mul_f32_e32 v148, v148, v214
	v_mul_f32_e32 v149, v149, v214
	v_mul_f32_e32 v150, v150, v214
	v_mul_f32_e32 v151, v151, v214
	v_mul_f32_e32 v152, v152, v214
	v_mul_f32_e32 v153, v153, v214
	v_mul_f32_e32 v154, v154, v214
	v_mul_f32_e32 v155, v155, v214
	v_mul_f32_e32 v156, v156, v214
	v_mul_f32_e32 v157, v157, v214
	v_mul_f32_e32 v158, v158, v214
	v_mul_f32_e32 v159, v159, v214
	v_mul_f32_e32 v160, v160, v214
	v_mul_f32_e32 v161, v161, v214
	v_mul_f32_e32 v162, v162, v214
	v_mul_f32_e32 v163, v163, v214
	v_mul_f32_e32 v148, v100, v148
	v_mul_f32_e32 v149, v101, v149
	v_mul_f32_e32 v150, v102, v150
	v_mul_f32_e32 v151, v103, v151
	v_mul_f32_e32 v152, v104, v152
	v_mul_f32_e32 v153, v105, v153
	v_mul_f32_e32 v154, v106, v154
	v_mul_f32_e32 v155, v107, v155
	v_mul_f32_e32 v156, v108, v156
	v_mul_f32_e32 v157, v109, v157
	v_mul_f32_e32 v158, v110, v158
	v_mul_f32_e32 v159, v111, v159
	v_mul_f32_e32 v160, v112, v160
	v_mul_f32_e32 v161, v113, v161
	v_mul_f32_e32 v162, v114, v162
	v_mul_f32_e32 v163, v115, v163
	v_cvt_pk_bf16_f32 v196, v148, v149
	v_cvt_pk_bf16_f32 v197, v150, v151
	v_cvt_pk_bf16_f32 v198, v152, v153
	v_cvt_pk_bf16_f32 v199, v154, v155
	v_cvt_pk_bf16_f32 v200, v156, v157
	v_cvt_pk_bf16_f32 v201, v158, v159
	v_cvt_pk_bf16_f32 v202, v160, v161
	v_cvt_pk_bf16_f32 v203, v162, v163
	global_store_dwordx4 v23, v[196:199], s[30:31]
	global_store_dwordx4 v23, v[200:203], s[30:31] offset:1024
	v_mul_f32_e32 v164, v164, v215
	v_mul_f32_e32 v165, v165, v215
	v_mul_f32_e32 v166, v166, v215
	v_mul_f32_e32 v167, v167, v215
	v_mul_f32_e32 v168, v168, v215
	v_mul_f32_e32 v169, v169, v215
	v_mul_f32_e32 v170, v170, v215
	v_mul_f32_e32 v171, v171, v215
	v_mul_f32_e32 v172, v172, v215
	v_mul_f32_e32 v173, v173, v215
	v_mul_f32_e32 v174, v174, v215
	v_mul_f32_e32 v175, v175, v215
	v_mul_f32_e32 v176, v176, v215
	v_mul_f32_e32 v177, v177, v215
	v_mul_f32_e32 v178, v178, v215
	v_mul_f32_e32 v179, v179, v215
	v_mul_f32_e32 v164, v100, v164
	v_mul_f32_e32 v165, v101, v165
	v_mul_f32_e32 v166, v102, v166
	v_mul_f32_e32 v167, v103, v167
	v_mul_f32_e32 v168, v104, v168
	v_mul_f32_e32 v169, v105, v169
	v_mul_f32_e32 v170, v106, v170
	v_mul_f32_e32 v171, v107, v171
	v_mul_f32_e32 v172, v108, v172
	v_mul_f32_e32 v173, v109, v173
	v_mul_f32_e32 v174, v110, v174
	v_mul_f32_e32 v175, v111, v175
	v_mul_f32_e32 v176, v112, v176
	v_mul_f32_e32 v177, v113, v177
	v_mul_f32_e32 v178, v114, v178
	v_mul_f32_e32 v179, v115, v179
	v_cvt_pk_bf16_f32 v204, v164, v165
	v_cvt_pk_bf16_f32 v205, v166, v167
	v_cvt_pk_bf16_f32 v206, v168, v169
	v_cvt_pk_bf16_f32 v207, v170, v171
	v_cvt_pk_bf16_f32 v208, v172, v173
	v_cvt_pk_bf16_f32 v209, v174, v175
	v_cvt_pk_bf16_f32 v210, v176, v177
	v_cvt_pk_bf16_f32 v211, v178, v179
	global_store_dwordx4 v23, v[204:207], s[30:31] offset:2048
	global_store_dwordx4 v23, v[208:211], s[30:31] offset:3072
	s_mov_b32 s16, s17
	s_branch .Lrms_loop1

.Lrms_loop1:
	s_add_i32 s17, s16, s10
	s_cmp_lt_u32 s17, s5
	s_cbranch_scc0 .Lrms_last1
	s_lshl_b32 s6, s17, 12
	s_add_u32 s18, s12, s6
	s_addc_u32 s19, s13, 0
	s_add_u32 s20, s18, 0x1000
	s_addc_u32 s21, s19, 0
	s_add_u32 s22, s20, 0x1000
	s_addc_u32 s23, s21, 0
	s_add_u32 s24, s22, 0x1000
	s_addc_u32 s25, s23, 0
	global_load_dwordx4 v[116:119], v22, s[18:19]
	global_load_dwordx4 v[120:123], v22, s[18:19] offset:16
	global_load_dwordx4 v[124:127], v22, s[18:19] offset:2048
	global_load_dwordx4 v[128:131], v22, s[18:19] offset:2064
	global_load_dwordx4 v[132:135], v22, s[20:21]
	global_load_dwordx4 v[136:139], v22, s[20:21] offset:16
	global_load_dwordx4 v[140:143], v22, s[20:21] offset:2048
	global_load_dwordx4 v[144:147], v22, s[20:21] offset:2064
	global_load_dwordx4 v[148:151], v22, s[22:23]
	global_load_dwordx4 v[152:155], v22, s[22:23] offset:16
	global_load_dwordx4 v[156:159], v22, s[22:23] offset:2048
	global_load_dwordx4 v[160:163], v22, s[22:23] offset:2064
	global_load_dwordx4 v[164:167], v22, s[24:25]
	global_load_dwordx4 v[168:171], v22, s[24:25] offset:16
	global_load_dwordx4 v[172:175], v22, s[24:25] offset:2048
	global_load_dwordx4 v[176:179], v22, s[24:25] offset:2064
	s_waitcnt vmcnt(24)
	v_mul_f32_e32 v8, v24, v24
	v_mul_f32_e32 v9, v40, v40
	v_mul_f32_e32 v10, v56, v56
	v_mul_f32_e32 v11, v72, v72
	v_fmac_f32_e32 v8, v25, v25
	v_fmac_f32_e32 v9, v41, v41
	v_fmac_f32_e32 v10, v57, v57
	v_fmac_f32_e32 v11, v73, v73
	v_fmac_f32_e32 v8, v26, v26
	v_fmac_f32_e32 v9, v42, v42
	v_fmac_f32_e32 v10, v58, v58
	v_fmac_f32_e32 v11, v74, v74
	v_fmac_f32_e32 v8, v27, v27
	v_fmac_f32_e32 v9, v43, v43
	v_fmac_f32_e32 v10, v59, v59
	v_fmac_f32_e32 v11, v75, v75
	v_fmac_f32_e32 v8, v28, v28
	v_fmac_f32_e32 v9, v44, v44
	v_fmac_f32_e32 v10, v60, v60
	v_fmac_f32_e32 v11, v76, v76
	v_fmac_f32_e32 v8, v29, v29
	v_fmac_f32_e32 v9, v45, v45
	v_fmac_f32_e32 v10, v61, v61
	v_fmac_f32_e32 v11, v77, v77
	v_fmac_f32_e32 v8, v30, v30
	v_fmac_f32_e32 v9, v46, v46
	v_fmac_f32_e32 v10, v62, v62
	v_fmac_f32_e32 v11, v78, v78
	v_fmac_f32_e32 v8, v31, v31
	v_fmac_f32_e32 v9, v47, v47
	v_fmac_f32_e32 v10, v63, v63
	v_fmac_f32_e32 v11, v79, v79
	v_fmac_f32_e32 v8, v32, v32
	v_fmac_f32_e32 v9, v48, v48
	v_fmac_f32_e32 v10, v64, v64
	v_fmac_f32_e32 v11, v80, v80
	v_fmac_f32_e32 v8, v33, v33
	v_fmac_f32_e32 v9, v49, v49
	v_fmac_f32_e32 v10, v65, v65
	v_fmac_f32_e32 v11, v81, v81
	v_fmac_f32_e32 v8, v34, v34
	v_fmac_f32_e32 v9, v50, v50
	v_fmac_f32_e32 v10, v66, v66
	v_fmac_f32_e32 v11, v82, v82
	v_fmac_f32_e32 v8, v35, v35
	v_fmac_f32_e32 v9, v51, v51
	v_fmac_f32_e32 v10, v67, v67
	v_fmac_f32_e32 v11, v83, v83
	v_fmac_f32_e32 v8, v36, v36
	v_fmac_f32_e32 v9, v52, v52
	v_fmac_f32_e32 v10, v68, v68
	v_fmac_f32_e32 v11, v84, v84
	v_fmac_f32_e32 v8, v37, v37
	v_fmac_f32_e32 v9, v53, v53
	v_fmac_f32_e32 v10, v69, v69
	v_fmac_f32_e32 v11, v85, v85
	v_fmac_f32_e32 v8, v38, v38
	v_fmac_f32_e32 v9, v54, v54
	v_fmac_f32_e32 v10, v70, v70
	v_fmac_f32_e32 v11, v86, v86
	v_fmac_f32_e32 v8, v39, v39
	v_fmac_f32_e32 v9, v55, v55
	v_fmac_f32_e32 v10, v71, v71
	v_fmac_f32_e32 v11, v87, v87
	ds_bpermute_b32 v12, v16, v8
	ds_bpermute_b32 v13, v16, v9
	ds_bpermute_b32 v14, v16, v10
	ds_bpermute_b32 v15, v16, v11
	s_waitcnt lgkmcnt(0)
	v_add_f32_e32 v8, v8, v12
	v_add_f32_e32 v9, v9, v13
	v_add_f32_e32 v10, v10, v14
	v_add_f32_e32 v11, v11, v15
	ds_bpermute_b32 v12, v17, v8
	ds_bpermute_b32 v13, v17, v9
	ds_bpermute_b32 v14, v17, v10
	ds_bpermute_b32 v15, v17, v11
	s_waitcnt lgkmcnt(0)
	v_add_f32_e32 v8, v8, v12
	v_add_f32_e32 v9, v9, v13
	v_add_f32_e32 v10, v10, v14
	v_add_f32_e32 v11, v11, v15
	ds_bpermute_b32 v12, v18, v8
	ds_bpermute_b32 v13, v18, v9
	ds_bpermute_b32 v14, v18, v10
	ds_bpermute_b32 v15, v18, v11
	s_waitcnt lgkmcnt(0)
	v_add_f32_e32 v8, v8, v12
	v_add_f32_e32 v9, v9, v13
	v_add_f32_e32 v10, v10, v14
	v_add_f32_e32 v11, v11, v15
	ds_bpermute_b32 v12, v19, v8
	ds_bpermute_b32 v13, v19, v9
	ds_bpermute_b32 v14, v19, v10
	ds_bpermute_b32 v15, v19, v11
	s_waitcnt lgkmcnt(0)
	v_add_f32_e32 v8, v8, v12
	v_add_f32_e32 v9, v9, v13
	v_add_f32_e32 v10, v10, v14
	v_add_f32_e32 v11, v11, v15
	ds_bpermute_b32 v12, v20, v8
	ds_bpermute_b32 v13, v20, v9
	ds_bpermute_b32 v14, v20, v10
	ds_bpermute_b32 v15, v20, v11
	s_waitcnt lgkmcnt(0)
	v_add_f32_e32 v8, v8, v12
	v_add_f32_e32 v9, v9, v13
	v_add_f32_e32 v10, v10, v14
	v_add_f32_e32 v11, v11, v15
	ds_bpermute_b32 v12, v21, v8
	ds_bpermute_b32 v13, v21, v9
	ds_bpermute_b32 v14, v21, v10
	ds_bpermute_b32 v15, v21, v11
	s_waitcnt lgkmcnt(0)
	v_add_f32_e32 v8, v8, v12
	v_add_f32_e32 v9, v9, v13
	v_add_f32_e32 v10, v10, v14
	v_add_f32_e32 v11, v11, v15
	v_fmamk_f32 v8, v8, 0x3a800000, v220
	v_fmamk_f32 v9, v9, 0x3a800000, v220
	v_fmamk_f32 v10, v10, 0x3a800000, v220
	v_fmamk_f32 v11, v11, 0x3a800000, v220
	v_mul_f32_e32 v12, 0x4b800000, v8
	v_mul_f32_e32 v13, 0x4b800000, v9
	v_mul_f32_e32 v14, 0x4b800000, v10
	v_mul_f32_e32 v15, 0x4b800000, v11
	v_cmp_gt_f32_e32 vcc, s7, v8
	s_nop 1
	v_cndmask_b32_e32 v8, v8, v12, vcc
	v_rsq_f32_e32 v212, v8
	s_nop 0
	v_mul_f32_e32 v216, 0x45800000, v212
	v_cndmask_b32_e32 v212, v212, v216, vcc
	v_cmp_gt_f32_e32 vcc, s7, v9
	s_nop 1
	v_cndmask_b32_e32 v9, v9, v13, vcc
	v_rsq_f32_e32 v213, v9
	s_nop 0
	v_mul_f32_e32 v216, 0x45800000, v213
	v_cndmask_b32_e32 v213, v213, v216, vcc
	v_cmp_gt_f32_e32 vcc, s7, v10
	s_nop 1
	v_cndmask_b32_e32 v10, v10, v14, vcc
	v_rsq_f32_e32 v214, v10
	s_nop 0
	v_mul_f32_e32 v216, 0x45800000, v214
	v_cndmask_b32_e32 v214, v214, v216, vcc
	v_cmp_gt_f32_e32 vcc, s7, v11
	s_nop 1
	v_cndmask_b32_e32 v11, v11, v15, vcc
	v_rsq_f32_e32 v215, v11
	s_nop 0
	v_mul_f32_e32 v216, 0x45800000, v215
	v_cndmask_b32_e32 v215, v215, v216, vcc
	s_lshl_b32 s6, s16, 11
	s_add_u32 s26, s46, s6
	s_addc_u32 s27, s47, 0
	s_add_u32 s30, s26, 0x1000
	s_addc_u32 s31, s27, 0
	v_mul_f32_e32 v24, v24, v212
	v_mul_f32_e32 v25, v25, v212
	v_mul_f32_e32 v26, v26, v212
	v_mul_f32_e32 v27, v27, v212
	v_mul_f32_e32 v28, v28, v212
	v_mul_f32_e32 v29, v29, v212
	v_mul_f32_e32 v30, v30, v212
	v_mul_f32_e32 v31, v31, v212
	v_mul_f32_e32 v32, v32, v212
	v_mul_f32_e32 v33, v33, v212
	v_mul_f32_e32 v34, v34, v212
	v_mul_f32_e32 v35, v35, v212
	v_mul_f32_e32 v36, v36, v212
	v_mul_f32_e32 v37, v37, v212
	v_mul_f32_e32 v38, v38, v212
	v_mul_f32_e32 v39, v39, v212
	v_mul_f32_e32 v24, v100, v24
	v_mul_f32_e32 v25, v101, v25
	v_mul_f32_e32 v26, v102, v26
	v_mul_f32_e32 v27, v103, v27
	v_mul_f32_e32 v28, v104, v28
	v_mul_f32_e32 v29, v105, v29
	v_mul_f32_e32 v30, v106, v30
	v_mul_f32_e32 v31, v107, v31
	v_mul_f32_e32 v32, v108, v32
	v_mul_f32_e32 v33, v109, v33
	v_mul_f32_e32 v34, v110, v34
	v_mul_f32_e32 v35, v111, v35
	v_mul_f32_e32 v36, v112, v36
	v_mul_f32_e32 v37, v113, v37
	v_mul_f32_e32 v38, v114, v38
	v_mul_f32_e32 v39, v115, v39
	v_cvt_pk_bf16_f32 v180, v24, v25
	v_cvt_pk_bf16_f32 v181, v26, v27
	v_cvt_pk_bf16_f32 v182, v28, v29
	v_cvt_pk_bf16_f32 v183, v30, v31
	v_cvt_pk_bf16_f32 v184, v32, v33
	v_cvt_pk_bf16_f32 v185, v34, v35
	v_cvt_pk_bf16_f32 v186, v36, v37
	v_cvt_pk_bf16_f32 v187, v38, v39
	global_store_dwordx4 v23, v[180:183], s[26:27]
	global_store_dwordx4 v23, v[184:187], s[26:27] offset:1024
	v_mul_f32_e32 v40, v40, v213
	v_mul_f32_e32 v41, v41, v213
	v_mul_f32_e32 v42, v42, v213
	v_mul_f32_e32 v43, v43, v213
	v_mul_f32_e32 v44, v44, v213
	v_mul_f32_e32 v45, v45, v213
	v_mul_f32_e32 v46, v46, v213
	v_mul_f32_e32 v47, v47, v213
	v_mul_f32_e32 v48, v48, v213
	v_mul_f32_e32 v49, v49, v213
	v_mul_f32_e32 v50, v50, v213
	v_mul_f32_e32 v51, v51, v213
	v_mul_f32_e32 v52, v52, v213
	v_mul_f32_e32 v53, v53, v213
	v_mul_f32_e32 v54, v54, v213
	v_mul_f32_e32 v55, v55, v213
	v_mul_f32_e32 v40, v100, v40
	v_mul_f32_e32 v41, v101, v41
	v_mul_f32_e32 v42, v102, v42
	v_mul_f32_e32 v43, v103, v43
	v_mul_f32_e32 v44, v104, v44
	v_mul_f32_e32 v45, v105, v45
	v_mul_f32_e32 v46, v106, v46
	v_mul_f32_e32 v47, v107, v47
	v_mul_f32_e32 v48, v108, v48
	v_mul_f32_e32 v49, v109, v49
	v_mul_f32_e32 v50, v110, v50
	v_mul_f32_e32 v51, v111, v51
	v_mul_f32_e32 v52, v112, v52
	v_mul_f32_e32 v53, v113, v53
	v_mul_f32_e32 v54, v114, v54
	v_mul_f32_e32 v55, v115, v55
	v_cvt_pk_bf16_f32 v188, v40, v41
	v_cvt_pk_bf16_f32 v189, v42, v43
	v_cvt_pk_bf16_f32 v190, v44, v45
	v_cvt_pk_bf16_f32 v191, v46, v47
	v_cvt_pk_bf16_f32 v192, v48, v49
	v_cvt_pk_bf16_f32 v193, v50, v51
	v_cvt_pk_bf16_f32 v194, v52, v53
	v_cvt_pk_bf16_f32 v195, v54, v55
	global_store_dwordx4 v23, v[188:191], s[26:27] offset:2048
	global_store_dwordx4 v23, v[192:195], s[26:27] offset:3072
	v_mul_f32_e32 v56, v56, v214
	v_mul_f32_e32 v57, v57, v214
	v_mul_f32_e32 v58, v58, v214
	v_mul_f32_e32 v59, v59, v214
	v_mul_f32_e32 v60, v60, v214
	v_mul_f32_e32 v61, v61, v214
	v_mul_f32_e32 v62, v62, v214
	v_mul_f32_e32 v63, v63, v214
	v_mul_f32_e32 v64, v64, v214
	v_mul_f32_e32 v65, v65, v214
	v_mul_f32_e32 v66, v66, v214
	v_mul_f32_e32 v67, v67, v214
	v_mul_f32_e32 v68, v68, v214
	v_mul_f32_e32 v69, v69, v214
	v_mul_f32_e32 v70, v70, v214
	v_mul_f32_e32 v71, v71, v214
	v_mul_f32_e32 v56, v100, v56
	v_mul_f32_e32 v57, v101, v57
	v_mul_f32_e32 v58, v102, v58
	v_mul_f32_e32 v59, v103, v59
	v_mul_f32_e32 v60, v104, v60
	v_mul_f32_e32 v61, v105, v61
	v_mul_f32_e32 v62, v106, v62
	v_mul_f32_e32 v63, v107, v63
	v_mul_f32_e32 v64, v108, v64
	v_mul_f32_e32 v65, v109, v65
	v_mul_f32_e32 v66, v110, v66
	v_mul_f32_e32 v67, v111, v67
	v_mul_f32_e32 v68, v112, v68
	v_mul_f32_e32 v69, v113, v69
	v_mul_f32_e32 v70, v114, v70
	v_mul_f32_e32 v71, v115, v71
	v_cvt_pk_bf16_f32 v196, v56, v57
	v_cvt_pk_bf16_f32 v197, v58, v59
	v_cvt_pk_bf16_f32 v198, v60, v61
	v_cvt_pk_bf16_f32 v199, v62, v63
	v_cvt_pk_bf16_f32 v200, v64, v65
	v_cvt_pk_bf16_f32 v201, v66, v67
	v_cvt_pk_bf16_f32 v202, v68, v69
	v_cvt_pk_bf16_f32 v203, v70, v71
	global_store_dwordx4 v23, v[196:199], s[30:31]
	global_store_dwordx4 v23, v[200:203], s[30:31] offset:1024
	v_mul_f32_e32 v72, v72, v215
	v_mul_f32_e32 v73, v73, v215
	v_mul_f32_e32 v74, v74, v215
	v_mul_f32_e32 v75, v75, v215
	v_mul_f32_e32 v76, v76, v215
	v_mul_f32_e32 v77, v77, v215
	v_mul_f32_e32 v78, v78, v215
	v_mul_f32_e32 v79, v79, v215
	v_mul_f32_e32 v80, v80, v215
	v_mul_f32_e32 v81, v81, v215
	v_mul_f32_e32 v82, v82, v215
	v_mul_f32_e32 v83, v83, v215
	v_mul_f32_e32 v84, v84, v215
	v_mul_f32_e32 v85, v85, v215
	v_mul_f32_e32 v86, v86, v215
	v_mul_f32_e32 v87, v87, v215
	v_mul_f32_e32 v72, v100, v72
	v_mul_f32_e32 v73, v101, v73
	v_mul_f32_e32 v74, v102, v74
	v_mul_f32_e32 v75, v103, v75
	v_mul_f32_e32 v76, v104, v76
	v_mul_f32_e32 v77, v105, v77
	v_mul_f32_e32 v78, v106, v78
	v_mul_f32_e32 v79, v107, v79
	v_mul_f32_e32 v80, v108, v80
	v_mul_f32_e32 v81, v109, v81
	v_mul_f32_e32 v82, v110, v82
	v_mul_f32_e32 v83, v111, v83
	v_mul_f32_e32 v84, v112, v84
	v_mul_f32_e32 v85, v113, v85
	v_mul_f32_e32 v86, v114, v86
	v_mul_f32_e32 v87, v115, v87
	v_cvt_pk_bf16_f32 v204, v72, v73
	v_cvt_pk_bf16_f32 v205, v74, v75
	v_cvt_pk_bf16_f32 v206, v76, v77
	v_cvt_pk_bf16_f32 v207, v78, v79
	v_cvt_pk_bf16_f32 v208, v80, v81
	v_cvt_pk_bf16_f32 v209, v82, v83
	v_cvt_pk_bf16_f32 v210, v84, v85
	v_cvt_pk_bf16_f32 v211, v86, v87
	global_store_dwordx4 v23, v[204:207], s[30:31] offset:2048
	global_store_dwordx4 v23, v[208:211], s[30:31] offset:3072
	s_mov_b32 s16, s17
	s_branch .Lrms_loop0

.Lrms_loop0:
	s_add_i32 s17, s16, s10
	s_cmp_lt_u32 s17, s5
	s_cbranch_scc0 .Lrms_last0
	s_lshl_b32 s6, s17, 12
	s_add_u32 s18, s12, s6
	s_addc_u32 s19, s13, 0
	s_add_u32 s20, s18, 0x1000
	s_addc_u32 s21, s19, 0
	s_add_u32 s22, s20, 0x1000
	s_addc_u32 s23, s21, 0
	s_add_u32 s24, s22, 0x1000
	s_addc_u32 s25, s23, 0
	global_load_dwordx4 v[24:27], v22, s[18:19]
	global_load_dwordx4 v[28:31], v22, s[18:19] offset:16
	global_load_dwordx4 v[32:35], v22, s[18:19] offset:2048
	global_load_dwordx4 v[36:39], v22, s[18:19] offset:2064
	global_load_dwordx4 v[40:43], v22, s[20:21]
	global_load_dwordx4 v[44:47], v22, s[20:21] offset:16
	global_load_dwordx4 v[48:51], v22, s[20:21] offset:2048
	global_load_dwordx4 v[52:55], v22, s[20:21] offset:2064
	global_load_dwordx4 v[56:59], v22, s[22:23]
	global_load_dwordx4 v[60:63], v22, s[22:23] offset:16
	global_load_dwordx4 v[64:67], v22, s[22:23] offset:2048
	global_load_dwordx4 v[68:71], v22, s[22:23] offset:2064
	global_load_dwordx4 v[72:75], v22, s[24:25]
	global_load_dwordx4 v[76:79], v22, s[24:25] offset:16
	global_load_dwordx4 v[80:83], v22, s[24:25] offset:2048
	global_load_dwordx4 v[84:87], v22, s[24:25] offset:2064
	s_waitcnt vmcnt(24)
	v_mul_f32_e32 v8, v116, v116
	v_mul_f32_e32 v9, v132, v132
	v_mul_f32_e32 v10, v148, v148
	v_mul_f32_e32 v11, v164, v164
	v_fmac_f32_e32 v8, v117, v117
	v_fmac_f32_e32 v9, v133, v133
	v_fmac_f32_e32 v10, v149, v149
	v_fmac_f32_e32 v11, v165, v165
	v_fmac_f32_e32 v8, v118, v118
	v_fmac_f32_e32 v9, v134, v134
	v_fmac_f32_e32 v10, v150, v150
	v_fmac_f32_e32 v11, v166, v166
	v_fmac_f32_e32 v8, v119, v119
	v_fmac_f32_e32 v9, v135, v135
	v_fmac_f32_e32 v10, v151, v151
	v_fmac_f32_e32 v11, v167, v167
	v_fmac_f32_e32 v8, v120, v120
	v_fmac_f32_e32 v9, v136, v136
	v_fmac_f32_e32 v10, v152, v152
	v_fmac_f32_e32 v11, v168, v168
	v_fmac_f32_e32 v8, v121, v121
	v_fmac_f32_e32 v9, v137, v137
	v_fmac_f32_e32 v10, v153, v153
	v_fmac_f32_e32 v11, v169, v169
	v_fmac_f32_e32 v8, v122, v122
	v_fmac_f32_e32 v9, v138, v138
	v_fmac_f32_e32 v10, v154, v154
	v_fmac_f32_e32 v11, v170, v170
	v_fmac_f32_e32 v8, v123, v123
	v_fmac_f32_e32 v9, v139, v139
	v_fmac_f32_e32 v10, v155, v155
	v_fmac_f32_e32 v11, v171, v171
	v_fmac_f32_e32 v8, v124, v124
	v_fmac_f32_e32 v9, v140, v140
	v_fmac_f32_e32 v10, v156, v156
	v_fmac_f32_e32 v11, v172, v172
	v_fmac_f32_e32 v8, v125, v125
	v_fmac_f32_e32 v9, v141, v141
	v_fmac_f32_e32 v10, v157, v157
	v_fmac_f32_e32 v11, v173, v173
	v_fmac_f32_e32 v8, v126, v126
	v_fmac_f32_e32 v9, v142, v142
	v_fmac_f32_e32 v10, v158, v158
	v_fmac_f32_e32 v11, v174, v174
	v_fmac_f32_e32 v8, v127, v127
	v_fmac_f32_e32 v9, v143, v143
	v_fmac_f32_e32 v10, v159, v159
	v_fmac_f32_e32 v11, v175, v175
	v_fmac_f32_e32 v8, v128, v128
	v_fmac_f32_e32 v9, v144, v144
	v_fmac_f32_e32 v10, v160, v160
	v_fmac_f32_e32 v11, v176, v176
	v_fmac_f32_e32 v8, v129, v129
	v_fmac_f32_e32 v9, v145, v145
	v_fmac_f32_e32 v10, v161, v161
	v_fmac_f32_e32 v11, v177, v177
	v_fmac_f32_e32 v8, v130, v130
	v_fmac_f32_e32 v9, v146, v146
	v_fmac_f32_e32 v10, v162, v162
	v_fmac_f32_e32 v11, v178, v178
	v_fmac_f32_e32 v8, v131, v131
	v_fmac_f32_e32 v9, v147, v147
	v_fmac_f32_e32 v10, v163, v163
	v_fmac_f32_e32 v11, v179, v179
	ds_bpermute_b32 v12, v16, v8
	ds_bpermute_b32 v13, v16, v9
	ds_bpermute_b32 v14, v16, v10
	ds_bpermute_b32 v15, v16, v11
	s_waitcnt lgkmcnt(0)
	v_add_f32_e32 v8, v8, v12
	v_add_f32_e32 v9, v9, v13
	v_add_f32_e32 v10, v10, v14
	v_add_f32_e32 v11, v11, v15
	ds_bpermute_b32 v12, v17, v8
	ds_bpermute_b32 v13, v17, v9
	ds_bpermute_b32 v14, v17, v10
	ds_bpermute_b32 v15, v17, v11
	s_waitcnt lgkmcnt(0)
	v_add_f32_e32 v8, v8, v12
	v_add_f32_e32 v9, v9, v13
	v_add_f32_e32 v10, v10, v14
	v_add_f32_e32 v11, v11, v15
	ds_bpermute_b32 v12, v18, v8
	ds_bpermute_b32 v13, v18, v9
	ds_bpermute_b32 v14, v18, v10
	ds_bpermute_b32 v15, v18, v11
	s_waitcnt lgkmcnt(0)
	v_add_f32_e32 v8, v8, v12
	v_add_f32_e32 v9, v9, v13
	v_add_f32_e32 v10, v10, v14
	v_add_f32_e32 v11, v11, v15
	ds_bpermute_b32 v12, v19, v8
	ds_bpermute_b32 v13, v19, v9
	ds_bpermute_b32 v14, v19, v10
	ds_bpermute_b32 v15, v19, v11
	s_waitcnt lgkmcnt(0)
	v_add_f32_e32 v8, v8, v12
	v_add_f32_e32 v9, v9, v13
	v_add_f32_e32 v10, v10, v14
	v_add_f32_e32 v11, v11, v15
	ds_bpermute_b32 v12, v20, v8
	ds_bpermute_b32 v13, v20, v9
	ds_bpermute_b32 v14, v20, v10
	ds_bpermute_b32 v15, v20, v11
	s_waitcnt lgkmcnt(0)
	v_add_f32_e32 v8, v8, v12
	v_add_f32_e32 v9, v9, v13
	v_add_f32_e32 v10, v10, v14
	v_add_f32_e32 v11, v11, v15
	ds_bpermute_b32 v12, v21, v8
	ds_bpermute_b32 v13, v21, v9
	ds_bpermute_b32 v14, v21, v10
	ds_bpermute_b32 v15, v21, v11
	s_waitcnt lgkmcnt(0)
	v_add_f32_e32 v8, v8, v12
	v_add_f32_e32 v9, v9, v13
	v_add_f32_e32 v10, v10, v14
	v_add_f32_e32 v11, v11, v15
	v_fmamk_f32 v8, v8, 0x3a800000, v220
	v_fmamk_f32 v9, v9, 0x3a800000, v220
	v_fmamk_f32 v10, v10, 0x3a800000, v220
	v_fmamk_f32 v11, v11, 0x3a800000, v220
	v_mul_f32_e32 v12, 0x4b800000, v8
	v_mul_f32_e32 v13, 0x4b800000, v9
	v_mul_f32_e32 v14, 0x4b800000, v10
	v_mul_f32_e32 v15, 0x4b800000, v11
	v_cmp_gt_f32_e32 vcc, s7, v8
	s_nop 1
	v_cndmask_b32_e32 v8, v8, v12, vcc
	v_rsq_f32_e32 v212, v8
	s_nop 0
	v_mul_f32_e32 v216, 0x45800000, v212
	v_cndmask_b32_e32 v212, v212, v216, vcc
	v_cmp_gt_f32_e32 vcc, s7, v9
	s_nop 1
	v_cndmask_b32_e32 v9, v9, v13, vcc
	v_rsq_f32_e32 v213, v9
	s_nop 0
	v_mul_f32_e32 v216, 0x45800000, v213
	v_cndmask_b32_e32 v213, v213, v216, vcc
	v_cmp_gt_f32_e32 vcc, s7, v10
	s_nop 1
	v_cndmask_b32_e32 v10, v10, v14, vcc
	v_rsq_f32_e32 v214, v10
	s_nop 0
	v_mul_f32_e32 v216, 0x45800000, v214
	v_cndmask_b32_e32 v214, v214, v216, vcc
	v_cmp_gt_f32_e32 vcc, s7, v11
	s_nop 1
	v_cndmask_b32_e32 v11, v11, v15, vcc
	v_rsq_f32_e32 v215, v11
	s_nop 0
	v_mul_f32_e32 v216, 0x45800000, v215
	v_cndmask_b32_e32 v215, v215, v216, vcc
	s_lshl_b32 s6, s16, 11
	s_add_u32 s26, s46, s6
	s_addc_u32 s27, s47, 0
	s_add_u32 s30, s26, 0x1000
	s_addc_u32 s31, s27, 0
	v_mul_f32_e32 v116, v116, v212
	v_mul_f32_e32 v117, v117, v212
	v_mul_f32_e32 v118, v118, v212
	v_mul_f32_e32 v119, v119, v212
	v_mul_f32_e32 v120, v120, v212
	v_mul_f32_e32 v121, v121, v212
	v_mul_f32_e32 v122, v122, v212
	v_mul_f32_e32 v123, v123, v212
	v_mul_f32_e32 v124, v124, v212
	v_mul_f32_e32 v125, v125, v212
	v_mul_f32_e32 v126, v126, v212
	v_mul_f32_e32 v127, v127, v212
	v_mul_f32_e32 v128, v128, v212
	v_mul_f32_e32 v129, v129, v212
	v_mul_f32_e32 v130, v130, v212
	v_mul_f32_e32 v131, v131, v212
	v_mul_f32_e32 v116, v100, v116
	v_mul_f32_e32 v117, v101, v117
	v_mul_f32_e32 v118, v102, v118
	v_mul_f32_e32 v119, v103, v119
	v_mul_f32_e32 v120, v104, v120
	v_mul_f32_e32 v121, v105, v121
	v_mul_f32_e32 v122, v106, v122
	v_mul_f32_e32 v123, v107, v123
	v_mul_f32_e32 v124, v108, v124
	v_mul_f32_e32 v125, v109, v125
	v_mul_f32_e32 v126, v110, v126
	v_mul_f32_e32 v127, v111, v127
	v_mul_f32_e32 v128, v112, v128
	v_mul_f32_e32 v129, v113, v129
	v_mul_f32_e32 v130, v114, v130
	v_mul_f32_e32 v131, v115, v131
	v_cvt_pk_bf16_f32 v180, v116, v117
	v_cvt_pk_bf16_f32 v181, v118, v119
	v_cvt_pk_bf16_f32 v182, v120, v121
	v_cvt_pk_bf16_f32 v183, v122, v123
	v_cvt_pk_bf16_f32 v184, v124, v125
	v_cvt_pk_bf16_f32 v185, v126, v127
	v_cvt_pk_bf16_f32 v186, v128, v129
	v_cvt_pk_bf16_f32 v187, v130, v131
	global_store_dwordx4 v23, v[180:183], s[26:27]
	global_store_dwordx4 v23, v[184:187], s[26:27] offset:1024
	v_mul_f32_e32 v132, v132, v213
	v_mul_f32_e32 v133, v133, v213
	v_mul_f32_e32 v134, v134, v213
	v_mul_f32_e32 v135, v135, v213
	v_mul_f32_e32 v136, v136, v213
	v_mul_f32_e32 v137, v137, v213
	v_mul_f32_e32 v138, v138, v213
	v_mul_f32_e32 v139, v139, v213
	v_mul_f32_e32 v140, v140, v213
	v_mul_f32_e32 v141, v141, v213
	v_mul_f32_e32 v142, v142, v213
	v_mul_f32_e32 v143, v143, v213
	v_mul_f32_e32 v144, v144, v213
	v_mul_f32_e32 v145, v145, v213
	v_mul_f32_e32 v146, v146, v213
	v_mul_f32_e32 v147, v147, v213
	v_mul_f32_e32 v132, v100, v132
	v_mul_f32_e32 v133, v101, v133
	v_mul_f32_e32 v134, v102, v134
	v_mul_f32_e32 v135, v103, v135
	v_mul_f32_e32 v136, v104, v136
	v_mul_f32_e32 v137, v105, v137
	v_mul_f32_e32 v138, v106, v138
	v_mul_f32_e32 v139, v107, v139
	v_mul_f32_e32 v140, v108, v140
	v_mul_f32_e32 v141, v109, v141
	v_mul_f32_e32 v142, v110, v142
	v_mul_f32_e32 v143, v111, v143
	v_mul_f32_e32 v144, v112, v144
	v_mul_f32_e32 v145, v113, v145
	v_mul_f32_e32 v146, v114, v146
	v_mul_f32_e32 v147, v115, v147
	v_cvt_pk_bf16_f32 v188, v132, v133
	v_cvt_pk_bf16_f32 v189, v134, v135
	v_cvt_pk_bf16_f32 v190, v136, v137
	v_cvt_pk_bf16_f32 v191, v138, v139
	v_cvt_pk_bf16_f32 v192, v140, v141
	v_cvt_pk_bf16_f32 v193, v142, v143
	v_cvt_pk_bf16_f32 v194, v144, v145
	v_cvt_pk_bf16_f32 v195, v146, v147
	global_store_dwordx4 v23, v[188:191], s[26:27] offset:2048
	global_store_dwordx4 v23, v[192:195], s[26:27] offset:3072
	v_mul_f32_e32 v148, v148, v214
	v_mul_f32_e32 v149, v149, v214
	v_mul_f32_e32 v150, v150, v214
	v_mul_f32_e32 v151, v151, v214
	v_mul_f32_e32 v152, v152, v214
	v_mul_f32_e32 v153, v153, v214
	v_mul_f32_e32 v154, v154, v214
	v_mul_f32_e32 v155, v155, v214
	v_mul_f32_e32 v156, v156, v214
	v_mul_f32_e32 v157, v157, v214
	v_mul_f32_e32 v158, v158, v214
	v_mul_f32_e32 v159, v159, v214
	v_mul_f32_e32 v160, v160, v214
	v_mul_f32_e32 v161, v161, v214
	v_mul_f32_e32 v162, v162, v214
	v_mul_f32_e32 v163, v163, v214
	v_mul_f32_e32 v148, v100, v148
	v_mul_f32_e32 v149, v101, v149
	v_mul_f32_e32 v150, v102, v150
	v_mul_f32_e32 v151, v103, v151
	v_mul_f32_e32 v152, v104, v152
	v_mul_f32_e32 v153, v105, v153
	v_mul_f32_e32 v154, v106, v154
	v_mul_f32_e32 v155, v107, v155
	v_mul_f32_e32 v156, v108, v156
	v_mul_f32_e32 v157, v109, v157
	v_mul_f32_e32 v158, v110, v158
	v_mul_f32_e32 v159, v111, v159
	v_mul_f32_e32 v160, v112, v160
	v_mul_f32_e32 v161, v113, v161
	v_mul_f32_e32 v162, v114, v162
	v_mul_f32_e32 v163, v115, v163
	v_cvt_pk_bf16_f32 v196, v148, v149
	v_cvt_pk_bf16_f32 v197, v150, v151
	v_cvt_pk_bf16_f32 v198, v152, v153
	v_cvt_pk_bf16_f32 v199, v154, v155
	v_cvt_pk_bf16_f32 v200, v156, v157
	v_cvt_pk_bf16_f32 v201, v158, v159
	v_cvt_pk_bf16_f32 v202, v160, v161
	v_cvt_pk_bf16_f32 v203, v162, v163
	global_store_dwordx4 v23, v[196:199], s[30:31]
	global_store_dwordx4 v23, v[200:203], s[30:31] offset:1024
	v_mul_f32_e32 v164, v164, v215
	v_mul_f32_e32 v165, v165, v215
	v_mul_f32_e32 v166, v166, v215
	v_mul_f32_e32 v167, v167, v215
	v_mul_f32_e32 v168, v168, v215
	v_mul_f32_e32 v169, v169, v215
	v_mul_f32_e32 v170, v170, v215
	v_mul_f32_e32 v171, v171, v215
	v_mul_f32_e32 v172, v172, v215
	v_mul_f32_e32 v173, v173, v215
	v_mul_f32_e32 v174, v174, v215
	v_mul_f32_e32 v175, v175, v215
	v_mul_f32_e32 v176, v176, v215
	v_mul_f32_e32 v177, v177, v215
	v_mul_f32_e32 v178, v178, v215
	v_mul_f32_e32 v179, v179, v215
	v_mul_f32_e32 v164, v100, v164
	v_mul_f32_e32 v165, v101, v165
	v_mul_f32_e32 v166, v102, v166
	v_mul_f32_e32 v167, v103, v167
	v_mul_f32_e32 v168, v104, v168
	v_mul_f32_e32 v169, v105, v169
	v_mul_f32_e32 v170, v106, v170
	v_mul_f32_e32 v171, v107, v171
	v_mul_f32_e32 v172, v108, v172
	v_mul_f32_e32 v173, v109, v173
	v_mul_f32_e32 v174, v110, v174
	v_mul_f32_e32 v175, v111, v175
	v_mul_f32_e32 v176, v112, v176
	v_mul_f32_e32 v177, v113, v177
	v_mul_f32_e32 v178, v114, v178
	v_mul_f32_e32 v179, v115, v179
	v_cvt_pk_bf16_f32 v204, v164, v165
	v_cvt_pk_bf16_f32 v205, v166, v167
	v_cvt_pk_bf16_f32 v206, v168, v169
	v_cvt_pk_bf16_f32 v207, v170, v171
	v_cvt_pk_bf16_f32 v208, v172, v173
	v_cvt_pk_bf16_f32 v209, v174, v175
	v_cvt_pk_bf16_f32 v210, v176, v177
	v_cvt_pk_bf16_f32 v211, v178, v179
	global_store_dwordx4 v23, v[204:207], s[30:31] offset:2048
	global_store_dwordx4 v23, v[208:211], s[30:31] offset:3072
	s_mov_b32 s16, s17
	s_branch .Lrms_loop1
